# waits at first consumer: counted vmcnt waits in the Gates and In1 epilogue heads instead of one vmcnt(0) behind the 8 batched row-sumsq loads
# speedup vs baseline: 1.0033x; 1.0033x over previous
; #define LAS __attribute__((address_space(3)))
; template <int NP> __device__ __forceinline__ void row_scales(float (&rs)[2][4], const float* base, long row0, int fq, float inv_n) {
;     float t[2][4];
; #pragma unroll
;     for (int ai = 0; ai < 2; ++ai)
; #pragma unroll
;         for (int m = 0; m < 4; ++m) { const long row = row0 + ai * 128 + m * 16;
;             if (NP == 16) { const f32x4 v = *(const f32x4*)(base + row * 16 + 4 * fq); t[ai][m] = (v.x + v.y) + (v.z + v.w); }
;             else if (NP == 8) { const f32x2 v = *(const f32x2*)(base + row * 8 + 2 * fq); t[ai][m] = v.x + v.y; }
;             else t[ai][m] = base[row * 4 + fq]; }
; #pragma unroll
;     for (int ai = 0; ai < 2; ++ai)
; #pragma unroll
;         for (int m = 0; m < 4; ++m) rs[ai][m] = rsqrtf(red_fq(t[ai][m]) * inv_n + EPS);
;     __device__ __forceinline__ void operator()(AccT& acc, const Unit& u, int wr, int wc, int fr, int fq, LAS unsigned char*) const {
;         const long row0 = (long)u.pm * 256 + wr * 64 + fr;
;         const size_t tb = ((size_t)(u.pm * 12 + u.pn) * 8 + (wr * 4 + wc)) * 16; const int lane = fq * 16 + fr;
;         float rsa[2][4]; row_scales<16>(rsa, ssqx, row0, fq, 1.f / 1024.f);
; #pragma unroll
;         for (int ai = 0; ai < 2; ++ai)
; #pragma unroll
;             for (int m = 0; m < 4; ++m) {
;                 const float rs = rsa[ai][m] * -LOG2E;
.LBB0_335:
	s_ashr_i32 s1, s0, 31
	s_mul_i32 s8, s0, 12
	s_lshl_b64 s[0:1], s[0:1], 14
	v_lshl_add_u64 v[144:145], v[134:135], 0, s[0:1]
	global_load_dwordx4 v[140:143], v[144:145], off
	s_add_i32 s8, s8, s79
	s_ashr_i32 s9, s8, 31
	s_lshl_b64 s[12:13], s[8:9], 17
	s_movk_i32 s8, 0x2000
	v_add_co_u32_e32 v162, vcc, s8, v144
	s_mov_b32 s0, 0x358637bd
	s_nop 0
	v_addc_co_u32_e32 v163, vcc, 0, v145, vcc
	global_load_dwordx4 v[156:159], v[162:163], off offset:2048
	global_load_dwordx4 v[164:167], v[144:145], off offset:1024
	global_load_dwordx4 v[168:171], v[144:145], off offset:2048
	global_load_dwordx4 v[172:175], v[144:145], off offset:3072
	global_load_dwordx4 v[176:179], v[162:163], off
	global_load_dwordx4 v[180:183], v[162:163], off offset:1024
	global_load_dwordx4 v[184:187], v[162:163], off offset:3072
	s_mov_b32 s18, 0x3a800000
	s_movk_i32 s75, 0xc0
	s_mov_b32 s26, 0x18000
	s_waitcnt vmcnt(7)
	v_mov_b32_e32 v146, v141
	v_mov_b32_e32 v147, v142
	v_mov_b32_e32 v141, v143
	v_pk_add_f32 v[140:141], v[146:147], v[140:141]
	s_nop 0
	v_pk_add_f32 v[150:151], v[140:141], v[140:141] op_sel:[0,1] op_sel_hi:[1,0]
	s_waitcnt vmcnt(5)
	v_mov_b64_e32 v[140:141], v[164:165]
	v_mov_b64_e32 v[142:143], v[166:167]
	v_mov_b32_e32 v146, v141
	v_mov_b32_e32 v147, v142
	v_mov_b32_e32 v141, v143
	v_pk_add_f32 v[140:141], v[146:147], v[140:141]
	s_nop 0
	v_pk_add_f32 v[160:161], v[140:141], v[140:141] op_sel:[0,1] op_sel_hi:[1,0]
	s_waitcnt vmcnt(4)
	v_mov_b64_e32 v[140:141], v[168:169]
	v_mov_b64_e32 v[142:143], v[170:171]
	v_mov_b32_e32 v146, v141
	v_mov_b32_e32 v147, v142
	v_mov_b32_e32 v141, v143
	v_pk_add_f32 v[140:141], v[146:147], v[140:141]
	s_nop 0
	v_pk_add_f32 v[152:153], v[140:141], v[140:141] op_sel:[0,1] op_sel_hi:[1,0]
	s_waitcnt vmcnt(3)
	v_mov_b64_e32 v[140:141], v[172:173]
	v_mov_b64_e32 v[142:143], v[174:175]
	v_mov_b32_e32 v146, v141
	v_mov_b32_e32 v147, v142
	v_mov_b32_e32 v141, v143
	v_pk_add_f32 v[140:141], v[146:147], v[140:141]
	s_nop 0
	v_pk_add_f32 v[148:149], v[140:141], v[140:141] op_sel:[0,1] op_sel_hi:[1,0]
	s_waitcnt vmcnt(2)
	v_mov_b64_e32 v[140:141], v[176:177]
	v_mov_b64_e32 v[142:143], v[178:179]
	v_mov_b32_e32 v144, v141
	v_mov_b32_e32 v145, v142
	v_mov_b32_e32 v141, v143
	v_pk_add_f32 v[140:141], v[144:145], v[140:141]
	s_waitcnt vmcnt(1)
	v_mov_b64_e32 v[144:145], v[180:181]
	v_mov_b64_e32 v[146:147], v[182:183]
	v_pk_add_f32 v[142:143], v[140:141], v[140:141] op_sel:[0,1] op_sel_hi:[1,0]
	v_mov_b32_e32 v140, v145
	v_mov_b32_e32 v141, v146
	v_mov_b32_e32 v145, v147
	v_pk_add_f32 v[140:141], v[140:141], v[144:145]
	s_nop 0
	v_pk_add_f32 v[146:147], v[140:141], v[140:141] op_sel:[0,1] op_sel_hi:[1,0]
	v_mov_b32_e32 v140, v157
	v_mov_b32_e32 v141, v158
	v_mov_b32_e32 v157, v159
	v_pk_add_f32 v[140:141], v[140:141], v[156:157]
	s_waitcnt vmcnt(0)
	v_mov_b64_e32 v[156:157], v[184:185]
	v_mov_b64_e32 v[158:159], v[186:187]
	v_pk_add_f32 v[140:141], v[140:141], v[140:141] op_sel:[0,1] op_sel_hi:[1,0]
	v_mov_b32_e32 v144, v157
	v_mov_b32_e32 v141, v150
	s_nop 1
	v_permlane16_swap_b32_e32 v150, v141
	v_add_f32_e32 v151, v150, v141
	v_mov_b32_e32 v141, v160
	s_nop 1
	v_permlane16_swap_b32_e32 v160, v141
	v_mov_b32_e32 v145, v158
	v_mov_b32_e32 v157, v159
	v_add_f32_e32 v150, v160, v141
	v_pk_add_f32 v[144:145], v[144:145], v[156:157]
	v_mov_b32_e32 v157, v151
	v_mov_b32_e32 v156, v150
	s_nop 0
	v_permlane32_swap_b32_e32 v151, v157
	v_permlane32_swap_b32_e32 v150, v156
	v_pk_add_f32 v[156:157], v[150:151], v[156:157]
	v_mov_b64_e32 v[150:151], s[0:1]
	v_pk_fma_f32 v[156:157], v[156:157], s[18:19], v[150:151] op_sel_hi:[1,0,0]
	v_pk_add_f32 v[144:145], v[144:145], v[144:145] op_sel:[0,1] op_sel_hi:[1,0]
	v_mul_f32_e32 v141, 0x4b800000, v157
	v_cmp_gt_f32_e64 s[0:1], s33, v157
	v_cmp_gt_f32_e32 vcc, s33, v156
	s_nop 0
	v_cndmask_b32_e64 v141, v157, v141, s[0:1]
	v_rsq_f32_e32 v141, v141
	s_nop 0
	v_mul_f32_e32 v143, 0x45800000, v141
	v_cndmask_b32_e64 v149, v141, v143, s[0:1]
	v_mul_f32_e32 v141, 0x4b800000, v156
	v_cndmask_b32_e32 v141, v156, v141, vcc
	v_rsq_f32_e32 v141, v141
	s_nop 0
	v_mul_f32_e32 v143, 0x45800000, v141
	v_cndmask_b32_e32 v147, v141, v143, vcc
	v_mov_b32_e32 v141, v152
	s_nop 1
	v_permlane16_swap_b32_e32 v152, v141
	v_add_f32_e32 v153, v152, v141
	v_mov_b32_e32 v141, v148
	s_nop 1
	v_permlane16_swap_b32_e32 v148, v141
	v_add_f32_e32 v152, v148, v141
	v_mov_b32_e32 v157, v153
	v_mov_b32_e32 v156, v152
	s_nop 0
	v_permlane32_swap_b32_e32 v153, v157
	v_permlane32_swap_b32_e32 v152, v156
	v_pk_add_f32 v[152:153], v[152:153], v[156:157]
	s_nop 0
	v_pk_fma_f32 v[152:153], v[152:153], s[18:19], v[150:151] op_sel_hi:[1,0,0]
	s_nop 0
	v_mul_f32_e32 v141, 0x4b800000, v153
	v_cmp_gt_f32_e64 s[0:1], s33, v153
	v_cmp_gt_f32_e32 vcc, s33, v152
	s_nop 0
	v_cndmask_b32_e64 v141, v153, v141, s[0:1]
	v_rsq_f32_e32 v141, v141
	s_nop 0
	v_mul_f32_e32 v143, 0x45800000, v141
	v_cndmask_b32_e64 v148, v141, v143, s[0:1]
	v_mul_f32_e32 v141, 0x4b800000, v152
	v_cndmask_b32_e32 v141, v152, v141, vcc
	v_rsq_f32_e32 v141, v141
	s_nop 0
	v_mul_f32_e32 v143, 0x45800000, v141
	v_cndmask_b32_e32 v145, v141, v143, vcc
	v_mov_b32_e32 v141, v142
	s_nop 1
	v_permlane16_swap_b32_e32 v142, v141
	v_add_f32_e32 v143, v142, v141
	v_mov_b32_e32 v141, v146
	s_nop 1
	v_permlane16_swap_b32_e32 v146, v141
	v_add_f32_e32 v142, v146, v141
	v_mov_b32_e32 v153, v143
	v_mov_b32_e32 v152, v142
	s_nop 0
	v_permlane32_swap_b32_e32 v143, v153
	v_permlane32_swap_b32_e32 v142, v152
	v_pk_add_f32 v[142:143], v[142:143], v[152:153]
	s_nop 0
	v_pk_fma_f32 v[142:143], v[142:143], s[18:19], v[150:151] op_sel_hi:[1,0,0]
	s_nop 0
	v_mul_f32_e32 v141, 0x4b800000, v143
; __device__ __forceinline__ unsigned pk2(float lo, float hi) { f32x2 v = {lo, hi}; bf16x2_t b = __builtin_convertvector(v, bf16x2_t); return __builtin_bit_cast(unsigned, b); }
; #define SG_(t) __builtin_amdgcn_rcpf(1.f + __builtin_amdgcn_exp2f(min2f(t, 19.931568f)))
; template <int NP> __device__ __forceinline__ void row_scales(float (&rs)[2][4], const float* base, long row0, int fq, float inv_n) {
;     float t[2][4];
; #pragma unroll
;     for (int ai = 0; ai < 2; ++ai)
; #pragma unroll
;         for (int m = 0; m < 4; ++m) { const long row = row0 + ai * 128 + m * 16;
;             if (NP == 16) { const f32x4 v = *(const f32x4*)(base + row * 16 + 4 * fq); t[ai][m] = (v.x + v.y) + (v.z + v.w); }
;             else if (NP == 8) { const f32x2 v = *(const f32x2*)(base + row * 8 + 2 * fq); t[ai][m] = v.x + v.y; }
;             else t[ai][m] = base[row * 4 + fq]; }
; #pragma unroll
;     for (int ai = 0; ai < 2; ++ai)
; #pragma unroll
;         for (int m = 0; m < 4; ++m) rs[ai][m] = rsqrtf(red_fq(t[ai][m]) * inv_n + EPS);
;     __device__ __forceinline__ void operator()(AccT& acc, const Unit& u, int wr, int wc, int fr, int fq, LAS unsigned char*) const {
;     ...
;             for (int m = 0; m < 4; ++m) {
;                 const float rs = rsa[ai][m] * -LOG2E;
;     ...
; #pragma unroll
;                 for (int bj = 0; bj < 2; ++bj) { const f32x4 v0 = acc[ai][bj][m][0] * rs, v1 = acc[ai][bj][m][1] * rs; u32x4 w;
;                     w.x = pk2(SG_(v0.x), SG_(v0.y)); w.y = pk2(SG_(v0.z), SG_(v0.w)); w.z = pk2(SG_(v1.x), SG_(v1.y)); w.w = pk2(SG_(v1.z), SG_(v1.w));
;     ...
;                     *(u32x4*)(gates + ((tb + (ai * 4 + m) * 2 + bj) * 64 + lane) * 8) = w; }
	v_cmp_gt_f32_e64 s[0:1], s33, v143
	v_cmp_gt_f32_e32 vcc, s33, v142
	s_nop 0
	v_cndmask_b32_e64 v141, v143, v141, s[0:1]
	v_rsq_f32_e32 v141, v141
	s_nop 0
	v_mul_f32_e32 v143, 0x45800000, v141
	v_cndmask_b32_e64 v143, v141, v143, s[0:1]
	v_mul_f32_e32 v141, 0x4b800000, v142
	v_cndmask_b32_e32 v141, v142, v141, vcc
	v_rsq_f32_e32 v141, v141
	s_nop 0
	v_mul_f32_e32 v142, 0x45800000, v141
	v_cndmask_b32_e32 v142, v141, v142, vcc
	v_mov_b32_e32 v141, v140
	s_nop 1
	v_permlane16_swap_b32_e32 v140, v141
	v_add_f32_e32 v141, v140, v141
	v_mov_b32_e32 v140, v144
	s_nop 1
	v_permlane16_swap_b32_e32 v144, v140
	v_add_f32_e32 v140, v144, v140
	v_mov_b32_e32 v153, v141
	v_mov_b32_e32 v152, v140
	s_nop 0
	v_permlane32_swap_b32_e32 v141, v153
	v_permlane32_swap_b32_e32 v140, v152
	v_pk_add_f32 v[140:141], v[140:141], v[152:153]
	s_nop 0
	v_pk_fma_f32 v[140:141], v[140:141], s[18:19], v[150:151] op_sel_hi:[1,0,0]
	s_nop 0
	v_mul_f32_e32 v144, 0x4b800000, v141
	v_cmp_gt_f32_e64 s[0:1], s33, v141
	v_cmp_gt_f32_e32 vcc, s33, v140
	s_nop 0
	v_cndmask_b32_e64 v141, v141, v144, s[0:1]
	v_rsq_f32_e32 v141, v141
	s_nop 0
	v_mul_f32_e32 v144, 0x45800000, v141
	v_cndmask_b32_e64 v141, v141, v144, s[0:1]
	v_mul_f32_e32 v144, 0x4b800000, v140
	v_cndmask_b32_e32 v140, v140, v144, vcc
	v_rsq_f32_e32 v140, v140
	s_add_u32 s0, s2, s12
	s_addc_u32 s1, s55, s13
	v_mul_f32_e32 v144, 0x45800000, v140
	v_cndmask_b32_e32 v140, v140, v144, vcc
	v_mul_f32_e32 v144, 0xbfb8aa3b, v149
	v_pk_mul_f32 v[126:127], v[126:127], v[144:145] op_sel_hi:[1,0]
	v_pk_mul_f32 v[150:151], v[124:125], v[144:145] op_sel_hi:[1,0]
	v_min_f32_e32 v124, v126, v246
	v_min_f32_e32 v125, v127, v246
	v_pk_mul_f32 v[122:123], v[122:123], v[144:145] op_sel_hi:[1,0]
	v_exp_f32_e32 v124, v124
	v_exp_f32_e32 v125, v125
	v_pk_mul_f32 v[128:129], v[128:129], v[144:145] op_sel_hi:[1,0]
	v_min_f32_e32 v122, v122, v246
	v_add_f32_e32 v124, 1.0, v124
	v_add_f32_e32 v125, 1.0, v125
	v_rcp_f32_e32 v124, v124
	v_rcp_f32_e32 v125, v125
	v_min_f32_e32 v126, v129, v246
	v_min_f32_e32 v123, v123, v246
	v_exp_f32_e32 v122, v122
	v_cvt_pk_bf16_f32 v124, v124, v125
	v_min_f32_e32 v125, v128, v246
	v_exp_f32_e32 v126, v126
	v_exp_f32_e32 v125, v125
	v_exp_f32_e32 v123, v123
	v_add_f32_e32 v122, 1.0, v122
	v_add_f32_e32 v126, 1.0, v126
	v_add_f32_e32 v125, 1.0, v125
	v_add_f32_e32 v123, 1.0, v123
	v_rcp_f32_e32 v125, v125
	v_rcp_f32_e32 v126, v126
	v_rcp_f32_e32 v122, v122
	v_rcp_f32_e32 v123, v123
	v_pk_mul_f32 v[118:119], v[118:119], v[144:145] op_sel_hi:[1,0]
	v_cvt_pk_bf16_f32 v125, v125, v126
	v_pk_mul_f32 v[120:121], v[120:121], v[144:145] op_sel_hi:[1,0]
	v_cvt_pk_bf16_f32 v126, v122, v123
	v_min_f32_e32 v122, v150, v246
	v_min_f32_e32 v123, v151, v246
	s_nop 0
	v_exp_f32_e32 v122, v122
	v_exp_f32_e32 v123, v123
	v_add_f32_e32 v122, 1.0, v122
	v_add_f32_e32 v123, 1.0, v123
	v_rcp_f32_e32 v122, v122
	v_rcp_f32_e32 v123, v123
	s_nop 0
	v_cvt_pk_bf16_f32 v127, v122, v123
	global_store_dwordx4 v0, v[124:127], s[0:1]
	v_lshl_add_u64 v[122:123], s[0:1], 0, v[0:1]
	s_nop 0
	v_pk_mul_f32 v[124:125], v[116:117], v[144:145] op_sel_hi:[1,0]
	v_pk_mul_f32 v[116:117], v[114:115], v[144:145] op_sel_hi:[1,0]
	v_min_f32_e32 v114, v118, v246
	v_min_f32_e32 v115, v119, v246
	v_min_f32_e32 v118, v121, v246
	s_nop 0
	v_exp_f32_e32 v114, v114
	v_exp_f32_e32 v115, v115
	v_min_f32_e32 v116, v116, v246
	v_min_f32_e32 v117, v117, v246
	v_add_f32_e32 v114, 1.0, v114
	v_add_f32_e32 v115, 1.0, v115
	v_rcp_f32_e32 v114, v114
	v_rcp_f32_e32 v115, v115
	v_exp_f32_e32 v118, v118
	v_exp_f32_e32 v116, v116
	v_exp_f32_e32 v117, v117
	v_cvt_pk_bf16_f32 v114, v114, v115
	v_min_f32_e32 v115, v120, v246
	v_add_f32_e32 v118, 1.0, v118
	v_exp_f32_e32 v115, v115
	v_add_f32_e32 v116, 1.0, v116
	v_add_f32_e32 v117, 1.0, v117
	v_rcp_f32_e32 v118, v118
	v_add_f32_e32 v115, 1.0, v115
	v_rcp_f32_e32 v115, v115
	v_rcp_f32_e32 v116, v116
	v_rcp_f32_e32 v117, v117
	v_cvt_pk_bf16_f32 v115, v115, v118
	v_min_f32_e32 v118, v125, v246
	v_cvt_pk_bf16_f32 v116, v116, v117
	v_min_f32_e32 v117, v124, v246
	v_exp_f32_e32 v118, v118
	v_exp_f32_e32 v117, v117
	v_add_f32_e32 v118, 1.0, v118
	v_add_f32_e32 v117, 1.0, v117
	v_rcp_f32_e32 v117, v117
	v_rcp_f32_e32 v118, v118
	s_nop 0
	v_cvt_pk_bf16_f32 v117, v117, v118
	global_store_dwordx4 v0, v[114:117], s[0:1] offset:1024
	s_nop 1
	v_mul_f32_e32 v114, 0xbfb8aa3b, v147
	v_pk_mul_f32 v[110:111], v[110:111], v[114:115] op_sel_hi:[1,0]
	v_pk_mul_f32 v[116:117], v[108:109], v[114:115] op_sel_hi:[1,0]
	v_pk_mul_f32 v[108:109], v[106:107], v[114:115] op_sel_hi:[1,0]
	v_min_f32_e32 v106, v110, v246
	v_min_f32_e32 v107, v111, v246
	v_pk_mul_f32 v[112:113], v[112:113], v[114:115] op_sel_hi:[1,0]
	v_exp_f32_e32 v106, v106
	v_exp_f32_e32 v107, v107
	v_min_f32_e32 v110, v113, v246
	v_min_f32_e32 v108, v108, v246
	v_add_f32_e32 v106, 1.0, v106
	v_add_f32_e32 v107, 1.0, v107
	v_rcp_f32_e32 v106, v106
	v_rcp_f32_e32 v107, v107
	v_min_f32_e32 v109, v109, v246
	v_exp_f32_e32 v110, v110
	v_exp_f32_e32 v108, v108
	v_cvt_pk_bf16_f32 v106, v106, v107
	v_min_f32_e32 v107, v112, v246
	v_exp_f32_e32 v109, v109
	v_exp_f32_e32 v107, v107
	v_add_f32_e32 v110, 1.0, v110
	v_add_f32_e32 v108, 1.0, v108
	v_add_f32_e32 v109, 1.0, v109
	v_add_f32_e32 v107, 1.0, v107
	v_rcp_f32_e32 v107, v107
	v_rcp_f32_e32 v110, v110
	v_rcp_f32_e32 v108, v108
	v_rcp_f32_e32 v109, v109
	v_pk_mul_f32 v[102:103], v[102:103], v[114:115] op_sel_hi:[1,0]
	v_cvt_pk_bf16_f32 v107, v107, v110
	v_min_f32_e32 v110, v117, v246
	v_cvt_pk_bf16_f32 v108, v108, v109
	v_min_f32_e32 v109, v116, v246
	v_exp_f32_e32 v110, v110
	v_exp_f32_e32 v109, v109
	v_pk_mul_f32 v[104:105], v[104:105], v[114:115] op_sel_hi:[1,0]
; __device__ __forceinline__ unsigned pk2(float lo, float hi) { f32x2 v = {lo, hi}; bf16x2_t b = __builtin_convertvector(v, bf16x2_t); return __builtin_bit_cast(unsigned, b); }
; #define SG_(t) __builtin_amdgcn_rcpf(1.f + __builtin_amdgcn_exp2f(min2f(t, 19.931568f)))
;     __device__ __forceinline__ void operator()(AccT& acc, const Unit& u, int wr, int wc, int fr, int fq, LAS unsigned char*) const {
;     ...
;             for (int m = 0; m < 4; ++m) {
;                 const float rs = rsa[ai][m] * -LOG2E;
;     ...
; #pragma unroll
;                 for (int bj = 0; bj < 2; ++bj) { const f32x4 v0 = acc[ai][bj][m][0] * rs, v1 = acc[ai][bj][m][1] * rs; u32x4 w;
;                     w.x = pk2(SG_(v0.x), SG_(v0.y)); w.y = pk2(SG_(v0.z), SG_(v0.w)); w.z = pk2(SG_(v1.x), SG_(v1.y)); w.w = pk2(SG_(v1.z), SG_(v1.w));
;     ...
;                     *(u32x4*)(gates + ((tb + (ai * 4 + m) * 2 + bj) * 64 + lane) * 8) = w; }
	v_add_f32_e32 v110, 1.0, v110
	v_add_f32_e32 v109, 1.0, v109
	v_rcp_f32_e32 v109, v109
	v_rcp_f32_e32 v110, v110
	s_nop 0
	v_cvt_pk_bf16_f32 v109, v109, v110
	global_store_dwordx4 v0, v[106:109], s[0:1] offset:2048
	s_nop 1
	v_pk_mul_f32 v[106:107], v[100:101], v[114:115] op_sel_hi:[1,0]
	v_pk_mul_f32 v[100:101], v[98:99], v[114:115] op_sel_hi:[1,0]
	v_min_f32_e32 v98, v102, v246
	v_min_f32_e32 v99, v103, v246
	v_min_f32_e32 v102, v105, v246
	s_nop 0
	v_exp_f32_e32 v98, v98
	v_exp_f32_e32 v99, v99
	v_min_f32_e32 v100, v100, v246
	v_min_f32_e32 v101, v101, v246
	v_add_f32_e32 v98, 1.0, v98
	v_add_f32_e32 v99, 1.0, v99
	v_rcp_f32_e32 v98, v98
	v_rcp_f32_e32 v99, v99
	v_exp_f32_e32 v102, v102
	v_exp_f32_e32 v100, v100
	v_exp_f32_e32 v101, v101
	v_cvt_pk_bf16_f32 v98, v98, v99
	v_min_f32_e32 v99, v104, v246
	v_add_f32_e32 v102, 1.0, v102
	v_exp_f32_e32 v99, v99
	v_add_f32_e32 v100, 1.0, v100
	v_add_f32_e32 v101, 1.0, v101
	v_rcp_f32_e32 v102, v102
	v_add_f32_e32 v99, 1.0, v99
	v_rcp_f32_e32 v99, v99
	v_rcp_f32_e32 v100, v100
	v_rcp_f32_e32 v101, v101
	v_cvt_pk_bf16_f32 v99, v99, v102
	v_min_f32_e32 v102, v107, v246
	v_cvt_pk_bf16_f32 v100, v100, v101
	v_min_f32_e32 v101, v106, v246
	v_exp_f32_e32 v102, v102
	v_exp_f32_e32 v101, v101
	v_add_f32_e32 v102, 1.0, v102
	v_add_f32_e32 v101, 1.0, v101
	v_rcp_f32_e32 v101, v101
	v_rcp_f32_e32 v102, v102
	s_nop 0
	v_cvt_pk_bf16_f32 v101, v101, v102
	global_store_dwordx4 v0, v[98:101], s[0:1] offset:3072
	s_movk_i32 s0, 0x1000
	s_nop 0
	v_mul_f32_e32 v98, 0xbfb8aa3b, v148
	v_pk_mul_f32 v[94:95], v[94:95], v[98:99] op_sel_hi:[1,0]
	v_pk_mul_f32 v[96:97], v[96:97], v[98:99] op_sel_hi:[1,0]
	v_min_f32_e32 v94, v94, v246
	v_min_f32_e32 v95, v95, v246
	v_pk_mul_f32 v[90:91], v[90:91], v[98:99] op_sel_hi:[1,0]
	v_exp_f32_e32 v94, v94
	v_exp_f32_e32 v95, v95
	v_min_f32_e32 v90, v90, v246
	v_min_f32_e32 v91, v91, v246
	v_add_f32_e32 v94, 1.0, v94
	v_add_f32_e32 v95, 1.0, v95
	v_rcp_f32_e32 v94, v94
	v_rcp_f32_e32 v95, v95
	v_exp_f32_e32 v90, v90
	v_exp_f32_e32 v91, v91
	v_pk_mul_f32 v[92:93], v[92:93], v[98:99] op_sel_hi:[1,0]
	v_cvt_pk_bf16_f32 v94, v94, v95
	v_min_f32_e32 v95, v96, v246
	v_min_f32_e32 v96, v97, v246
	v_add_f32_e32 v90, 1.0, v90
	v_exp_f32_e32 v95, v95
	v_exp_f32_e32 v96, v96
	v_add_f32_e32 v91, 1.0, v91
	v_rcp_f32_e32 v90, v90
	v_add_f32_e32 v95, 1.0, v95
	v_add_f32_e32 v96, 1.0, v96
	v_rcp_f32_e32 v95, v95
	v_rcp_f32_e32 v96, v96
	v_rcp_f32_e32 v91, v91
	v_pk_mul_f32 v[86:87], v[86:87], v[98:99] op_sel_hi:[1,0]
	v_pk_mul_f32 v[88:89], v[88:89], v[98:99] op_sel_hi:[1,0]
	v_cvt_pk_bf16_f32 v95, v95, v96
	v_cvt_pk_bf16_f32 v96, v90, v91
	v_min_f32_e32 v90, v92, v246
	v_min_f32_e32 v91, v93, v246
	v_add_co_u32_e32 v92, vcc, s0, v122
	v_exp_f32_e32 v90, v90
	v_exp_f32_e32 v91, v91
	v_addc_co_u32_e32 v93, vcc, 0, v123, vcc
	v_add_f32_e32 v90, 1.0, v90
	v_add_f32_e32 v91, 1.0, v91
	v_rcp_f32_e32 v90, v90
	v_rcp_f32_e32 v91, v91
	s_movk_i32 s0, 0x3000
	v_cvt_pk_bf16_f32 v97, v90, v91
	v_add_co_u32_e32 v90, vcc, s8, v122
	s_nop 1
	v_addc_co_u32_e32 v91, vcc, 0, v123, vcc
	global_store_dwordx4 v[90:91], v[94:97], off offset:-4096
	s_nop 1
	v_pk_mul_f32 v[94:95], v[84:85], v[98:99] op_sel_hi:[1,0]
	v_pk_mul_f32 v[84:85], v[82:83], v[98:99] op_sel_hi:[1,0]
	v_min_f32_e32 v82, v86, v246
	v_min_f32_e32 v83, v87, v246
	v_min_f32_e32 v86, v89, v246
	s_nop 0
	v_exp_f32_e32 v82, v82
	v_exp_f32_e32 v83, v83
	v_min_f32_e32 v84, v84, v246
	v_min_f32_e32 v85, v85, v246
	v_add_f32_e32 v82, 1.0, v82
	v_add_f32_e32 v83, 1.0, v83
	v_rcp_f32_e32 v82, v82
	v_rcp_f32_e32 v83, v83
	v_exp_f32_e32 v86, v86
	v_exp_f32_e32 v84, v84
	v_exp_f32_e32 v85, v85
	v_cvt_pk_bf16_f32 v82, v82, v83
	v_min_f32_e32 v83, v88, v246
	v_add_f32_e32 v86, 1.0, v86
	v_exp_f32_e32 v83, v83
	v_add_f32_e32 v84, 1.0, v84
	v_add_f32_e32 v85, 1.0, v85
	v_rcp_f32_e32 v86, v86
	v_add_f32_e32 v83, 1.0, v83
	v_rcp_f32_e32 v83, v83
	v_rcp_f32_e32 v84, v84
	v_rcp_f32_e32 v85, v85
	v_cvt_pk_bf16_f32 v83, v83, v86
	v_min_f32_e32 v86, v95, v246
	v_cvt_pk_bf16_f32 v84, v84, v85
	v_min_f32_e32 v85, v94, v246
	v_exp_f32_e32 v86, v86
	v_exp_f32_e32 v85, v85
	v_add_f32_e32 v86, 1.0, v86
	v_add_f32_e32 v85, 1.0, v85
	v_rcp_f32_e32 v85, v85
	v_rcp_f32_e32 v86, v86
	s_nop 0
	v_cvt_pk_bf16_f32 v85, v85, v86
	global_store_dwordx4 v[92:93], v[82:85], off offset:1024
	s_nop 1
	v_mul_f32_e32 v82, 0xbfb8aa3b, v145
	v_pk_mul_f32 v[78:79], v[78:79], v[82:83] op_sel_hi:[1,0]
	v_pk_mul_f32 v[84:85], v[76:77], v[82:83] op_sel_hi:[1,0]
	v_pk_mul_f32 v[76:77], v[74:75], v[82:83] op_sel_hi:[1,0]
	v_min_f32_e32 v74, v78, v246
	v_min_f32_e32 v75, v79, v246
	v_pk_mul_f32 v[80:81], v[80:81], v[82:83] op_sel_hi:[1,0]
	v_exp_f32_e32 v74, v74
	v_exp_f32_e32 v75, v75
	v_min_f32_e32 v78, v81, v246
	v_min_f32_e32 v76, v76, v246
	v_add_f32_e32 v74, 1.0, v74
	v_add_f32_e32 v75, 1.0, v75
	v_rcp_f32_e32 v74, v74
	v_rcp_f32_e32 v75, v75
	v_min_f32_e32 v77, v77, v246
	v_exp_f32_e32 v78, v78
	v_exp_f32_e32 v76, v76
	v_cvt_pk_bf16_f32 v74, v74, v75
	v_min_f32_e32 v75, v80, v246
	v_exp_f32_e32 v77, v77
	v_exp_f32_e32 v75, v75
	v_add_f32_e32 v78, 1.0, v78
	v_add_f32_e32 v76, 1.0, v76
	v_add_f32_e32 v77, 1.0, v77
	v_add_f32_e32 v75, 1.0, v75
	v_rcp_f32_e32 v75, v75
	v_rcp_f32_e32 v78, v78
	v_rcp_f32_e32 v76, v76
	v_rcp_f32_e32 v77, v77
	v_pk_mul_f32 v[70:71], v[70:71], v[82:83] op_sel_hi:[1,0]
	v_cvt_pk_bf16_f32 v75, v75, v78
	v_min_f32_e32 v78, v85, v246
	v_cvt_pk_bf16_f32 v76, v76, v77
	v_min_f32_e32 v77, v84, v246
	v_exp_f32_e32 v78, v78
	v_exp_f32_e32 v77, v77
	v_pk_mul_f32 v[72:73], v[72:73], v[82:83] op_sel_hi:[1,0]
	v_add_f32_e32 v78, 1.0, v78
	v_add_f32_e32 v77, 1.0, v77
	v_rcp_f32_e32 v77, v77
; __device__ __forceinline__ unsigned pk2(float lo, float hi) { f32x2 v = {lo, hi}; bf16x2_t b = __builtin_convertvector(v, bf16x2_t); return __builtin_bit_cast(unsigned, b); }
; #define SG_(t) __builtin_amdgcn_rcpf(1.f + __builtin_amdgcn_exp2f(min2f(t, 19.931568f)))
;     __device__ __forceinline__ void operator()(AccT& acc, const Unit& u, int wr, int wc, int fr, int fq, LAS unsigned char*) const {
;     ...
;             for (int m = 0; m < 4; ++m) {
;                 const float rs = rsa[ai][m] * -LOG2E;
;     ...
; #pragma unroll
;                 for (int bj = 0; bj < 2; ++bj) { const f32x4 v0 = acc[ai][bj][m][0] * rs, v1 = acc[ai][bj][m][1] * rs; u32x4 w;
;                     w.x = pk2(SG_(v0.x), SG_(v0.y)); w.y = pk2(SG_(v0.z), SG_(v0.w)); w.z = pk2(SG_(v1.x), SG_(v1.y)); w.w = pk2(SG_(v1.z), SG_(v1.w));
;     ...
;                     *(u32x4*)(gates + ((tb + (ai * 4 + m) * 2 + bj) * 64 + lane) * 8) = w; }
	v_rcp_f32_e32 v78, v78
	s_nop 0
	v_cvt_pk_bf16_f32 v77, v77, v78
	global_store_dwordx4 v[92:93], v[74:77], off offset:2048
	s_nop 1
	v_pk_mul_f32 v[74:75], v[68:69], v[82:83] op_sel_hi:[1,0]
	v_pk_mul_f32 v[68:69], v[66:67], v[82:83] op_sel_hi:[1,0]
	v_min_f32_e32 v66, v70, v246
	v_min_f32_e32 v67, v71, v246
	v_min_f32_e32 v70, v73, v246
	s_nop 0
	v_exp_f32_e32 v66, v66
	v_exp_f32_e32 v67, v67
	v_min_f32_e32 v68, v68, v246
	v_min_f32_e32 v69, v69, v246
	v_add_f32_e32 v66, 1.0, v66
	v_add_f32_e32 v67, 1.0, v67
	v_rcp_f32_e32 v66, v66
	v_rcp_f32_e32 v67, v67
	v_exp_f32_e32 v70, v70
	v_exp_f32_e32 v68, v68
	v_exp_f32_e32 v69, v69
	v_cvt_pk_bf16_f32 v66, v66, v67
	v_min_f32_e32 v67, v72, v246
	v_add_f32_e32 v70, 1.0, v70
	v_exp_f32_e32 v67, v67
	v_add_f32_e32 v68, 1.0, v68
	v_add_f32_e32 v69, 1.0, v69
	v_rcp_f32_e32 v70, v70
	v_add_f32_e32 v67, 1.0, v67
	v_rcp_f32_e32 v67, v67
	v_rcp_f32_e32 v68, v68
	v_rcp_f32_e32 v69, v69
	v_cvt_pk_bf16_f32 v67, v67, v70
	v_min_f32_e32 v70, v75, v246
	v_cvt_pk_bf16_f32 v68, v68, v69
	v_min_f32_e32 v69, v74, v246
	v_exp_f32_e32 v70, v70
	v_exp_f32_e32 v69, v69
	v_add_f32_e32 v70, 1.0, v70
	v_add_f32_e32 v69, 1.0, v69
	v_rcp_f32_e32 v69, v69
	v_rcp_f32_e32 v70, v70
	s_nop 0
	v_cvt_pk_bf16_f32 v69, v69, v70
	global_store_dwordx4 v[92:93], v[66:69], off offset:3072
	s_nop 1
	v_mul_f32_e32 v66, 0xbfb8aa3b, v143
	v_pk_mul_f32 v[62:63], v[62:63], v[66:67] op_sel_hi:[1,0]
	v_pk_mul_f32 v[68:69], v[60:61], v[66:67] op_sel_hi:[1,0]
	v_pk_mul_f32 v[60:61], v[58:59], v[66:67] op_sel_hi:[1,0]
	v_min_f32_e32 v58, v62, v246
	v_min_f32_e32 v59, v63, v246
	v_pk_mul_f32 v[64:65], v[64:65], v[66:67] op_sel_hi:[1,0]
	v_exp_f32_e32 v58, v58
	v_exp_f32_e32 v59, v59
	v_min_f32_e32 v62, v65, v246
	v_min_f32_e32 v60, v60, v246
	v_add_f32_e32 v58, 1.0, v58
	v_add_f32_e32 v59, 1.0, v59
	v_rcp_f32_e32 v58, v58
	v_rcp_f32_e32 v59, v59
	v_min_f32_e32 v61, v61, v246
	v_exp_f32_e32 v62, v62
	v_exp_f32_e32 v60, v60
	v_cvt_pk_bf16_f32 v58, v58, v59
	v_min_f32_e32 v59, v64, v246
	v_exp_f32_e32 v61, v61
	v_exp_f32_e32 v59, v59
	v_add_f32_e32 v62, 1.0, v62
	v_add_f32_e32 v60, 1.0, v60
	v_add_f32_e32 v61, 1.0, v61
	v_add_f32_e32 v59, 1.0, v59
	v_rcp_f32_e32 v59, v59
	v_rcp_f32_e32 v62, v62
	v_rcp_f32_e32 v60, v60
	v_rcp_f32_e32 v61, v61
	v_pk_mul_f32 v[54:55], v[54:55], v[66:67] op_sel_hi:[1,0]
	v_cvt_pk_bf16_f32 v59, v59, v62
	v_min_f32_e32 v62, v69, v246
	v_cvt_pk_bf16_f32 v60, v60, v61
	v_min_f32_e32 v61, v68, v246
	v_exp_f32_e32 v62, v62
	v_exp_f32_e32 v61, v61
	v_pk_mul_f32 v[56:57], v[56:57], v[66:67] op_sel_hi:[1,0]
	v_add_f32_e32 v62, 1.0, v62
	v_add_f32_e32 v61, 1.0, v61
	v_rcp_f32_e32 v61, v61
	v_rcp_f32_e32 v62, v62
	s_nop 0
	v_cvt_pk_bf16_f32 v61, v61, v62
	global_store_dwordx4 v[90:91], v[58:61], off
	s_nop 1
	v_pk_mul_f32 v[58:59], v[52:53], v[66:67] op_sel_hi:[1,0]
	v_pk_mul_f32 v[52:53], v[50:51], v[66:67] op_sel_hi:[1,0]
	v_min_f32_e32 v50, v54, v246
	v_min_f32_e32 v51, v55, v246
	v_min_f32_e32 v54, v57, v246
	s_nop 0
	v_exp_f32_e32 v50, v50
	v_exp_f32_e32 v51, v51
	v_min_f32_e32 v52, v52, v246
	v_min_f32_e32 v53, v53, v246
	v_add_f32_e32 v50, 1.0, v50
	v_add_f32_e32 v51, 1.0, v51
	v_rcp_f32_e32 v50, v50
	v_rcp_f32_e32 v51, v51
	v_exp_f32_e32 v54, v54
	v_exp_f32_e32 v52, v52
	v_exp_f32_e32 v53, v53
	v_cvt_pk_bf16_f32 v50, v50, v51
	v_min_f32_e32 v51, v56, v246
	v_add_f32_e32 v54, 1.0, v54
	v_exp_f32_e32 v51, v51
	v_add_f32_e32 v52, 1.0, v52
	v_add_f32_e32 v53, 1.0, v53
	v_rcp_f32_e32 v54, v54
	v_add_f32_e32 v51, 1.0, v51
	v_rcp_f32_e32 v51, v51
	v_rcp_f32_e32 v52, v52
	v_rcp_f32_e32 v53, v53
	v_cvt_pk_bf16_f32 v51, v51, v54
	v_min_f32_e32 v54, v59, v246
	v_cvt_pk_bf16_f32 v52, v52, v53
	v_min_f32_e32 v53, v58, v246
	v_exp_f32_e32 v54, v54
	v_exp_f32_e32 v53, v53
	v_add_f32_e32 v54, 1.0, v54
	v_add_f32_e32 v53, 1.0, v53
	v_rcp_f32_e32 v53, v53
	v_rcp_f32_e32 v54, v54
	s_nop 0
	v_cvt_pk_bf16_f32 v53, v53, v54
	global_store_dwordx4 v[90:91], v[50:53], off offset:1024
	s_nop 1
	v_mul_f32_e32 v50, 0xbfb8aa3b, v142
	v_pk_mul_f32 v[46:47], v[46:47], v[50:51] op_sel_hi:[1,0]
	v_pk_mul_f32 v[52:53], v[44:45], v[50:51] op_sel_hi:[1,0]
	v_pk_mul_f32 v[44:45], v[42:43], v[50:51] op_sel_hi:[1,0]
	v_min_f32_e32 v42, v46, v246
	v_min_f32_e32 v43, v47, v246
	v_pk_mul_f32 v[48:49], v[48:49], v[50:51] op_sel_hi:[1,0]
	v_exp_f32_e32 v42, v42
	v_exp_f32_e32 v43, v43
	v_min_f32_e32 v46, v49, v246
	v_min_f32_e32 v44, v44, v246
	v_add_f32_e32 v42, 1.0, v42
	v_add_f32_e32 v43, 1.0, v43
	v_rcp_f32_e32 v42, v42
	v_rcp_f32_e32 v43, v43
	v_min_f32_e32 v45, v45, v246
	v_exp_f32_e32 v46, v46
	v_exp_f32_e32 v44, v44
	v_cvt_pk_bf16_f32 v42, v42, v43
	v_min_f32_e32 v43, v48, v246
	v_exp_f32_e32 v45, v45
	v_exp_f32_e32 v43, v43
	v_add_f32_e32 v46, 1.0, v46
	v_add_f32_e32 v44, 1.0, v44
	v_add_f32_e32 v45, 1.0, v45
	v_add_f32_e32 v43, 1.0, v43
	v_rcp_f32_e32 v43, v43
	v_rcp_f32_e32 v46, v46
	v_rcp_f32_e32 v44, v44
	v_rcp_f32_e32 v45, v45
	v_pk_mul_f32 v[38:39], v[38:39], v[50:51] op_sel_hi:[1,0]
	v_cvt_pk_bf16_f32 v43, v43, v46
	v_min_f32_e32 v46, v53, v246
	v_cvt_pk_bf16_f32 v44, v44, v45
	v_min_f32_e32 v45, v52, v246
	v_exp_f32_e32 v46, v46
	v_exp_f32_e32 v45, v45
	v_pk_mul_f32 v[40:41], v[40:41], v[50:51] op_sel_hi:[1,0]
	v_add_f32_e32 v46, 1.0, v46
	v_add_f32_e32 v45, 1.0, v45
	v_rcp_f32_e32 v45, v45
	v_rcp_f32_e32 v46, v46
	s_nop 0
	v_cvt_pk_bf16_f32 v45, v45, v46
	global_store_dwordx4 v[90:91], v[42:45], off offset:2048
	s_nop 1
	v_pk_mul_f32 v[42:43], v[36:37], v[50:51] op_sel_hi:[1,0]
	v_pk_mul_f32 v[36:37], v[34:35], v[50:51] op_sel_hi:[1,0]
	v_min_f32_e32 v34, v38, v246
	v_min_f32_e32 v35, v39, v246
	v_min_f32_e32 v38, v41, v246
	s_nop 0
; __device__ __forceinline__ unsigned pk2(float lo, float hi) { f32x2 v = {lo, hi}; bf16x2_t b = __builtin_convertvector(v, bf16x2_t); return __builtin_bit_cast(unsigned, b); }
; #define PG8_BAR __builtin_amdgcn_s_barrier()
; #define SG_(t) __builtin_amdgcn_rcpf(1.f + __builtin_amdgcn_exp2f(min2f(t, 19.931568f)))
; template <class Epi>
; __device__ __forceinline__ void gemm_phase(LAS unsigned char* lds, const Gemm g, const Sched& S, const Epi& E) {
;     ...
;         if (!has_next) break;
;         if constexpr (!Epi::KEEP_ACC) {
; #pragma unroll
;         for (int a = 0; a < 2; ++a)
; #pragma unroll
;             for (int b = 0; b < 2; ++b)
; #pragma unroll
;                 for (int m = 0; m < 4; ++m)
; #pragma unroll
;                     for (int n = 0; n < 2; ++n) acc[a][b][m][n] = (f32x4){0.f, 0.f, 0.f, 0.f};
;         }
;         cur = nxt; cA = nA; cB = nB; ++ui; csp = nsp; chA = nhA;
;         if (wr == 1) PG8_BAR;
;     __device__ __forceinline__ void operator()(AccT& acc, const Unit& u, int wr, int wc, int fr, int fq, LAS unsigned char*) const {
;     ...
;             for (int m = 0; m < 4; ++m) {
;                 const float rs = rsa[ai][m] * -LOG2E;
;     ...
; #pragma unroll
;                 for (int bj = 0; bj < 2; ++bj) { const f32x4 v0 = acc[ai][bj][m][0] * rs, v1 = acc[ai][bj][m][1] * rs; u32x4 w;
;                     w.x = pk2(SG_(v0.x), SG_(v0.y)); w.y = pk2(SG_(v0.z), SG_(v0.w)); w.z = pk2(SG_(v1.x), SG_(v1.y)); w.w = pk2(SG_(v1.z), SG_(v1.w));
;     ...
;                     *(u32x4*)(gates + ((tb + (ai * 4 + m) * 2 + bj) * 64 + lane) * 8) = w; }
	v_exp_f32_e32 v34, v34
	v_exp_f32_e32 v35, v35
	v_min_f32_e32 v36, v36, v246
	v_min_f32_e32 v37, v37, v246
	v_add_f32_e32 v34, 1.0, v34
	v_add_f32_e32 v35, 1.0, v35
	v_rcp_f32_e32 v34, v34
	v_rcp_f32_e32 v35, v35
	v_exp_f32_e32 v38, v38
	v_exp_f32_e32 v36, v36
	v_exp_f32_e32 v37, v37
	v_cvt_pk_bf16_f32 v34, v34, v35
	v_min_f32_e32 v35, v40, v246
	v_add_f32_e32 v38, 1.0, v38
	v_exp_f32_e32 v35, v35
	v_add_f32_e32 v36, 1.0, v36
	v_add_f32_e32 v37, 1.0, v37
	v_rcp_f32_e32 v38, v38
	v_add_f32_e32 v35, 1.0, v35
	v_rcp_f32_e32 v35, v35
	v_rcp_f32_e32 v36, v36
	v_rcp_f32_e32 v37, v37
	v_cvt_pk_bf16_f32 v35, v35, v38
	v_min_f32_e32 v38, v43, v246
	v_cvt_pk_bf16_f32 v36, v36, v37
	v_min_f32_e32 v37, v42, v246
	v_exp_f32_e32 v38, v38
	v_exp_f32_e32 v37, v37
	v_add_f32_e32 v38, 1.0, v38
	v_add_f32_e32 v37, 1.0, v37
	v_rcp_f32_e32 v37, v37
	v_rcp_f32_e32 v38, v38
	s_nop 0
	v_cvt_pk_bf16_f32 v37, v37, v38
	global_store_dwordx4 v[90:91], v[34:37], off offset:3072
	s_nop 1
	v_mul_f32_e32 v34, 0xbfb8aa3b, v141
	v_pk_mul_f32 v[30:31], v[30:31], v[34:35] op_sel_hi:[1,0]
	v_pk_mul_f32 v[36:37], v[28:29], v[34:35] op_sel_hi:[1,0]
	v_min_f32_e32 v28, v30, v246
	v_min_f32_e32 v29, v31, v246
	v_pk_mul_f32 v[26:27], v[26:27], v[34:35] op_sel_hi:[1,0]
	v_exp_f32_e32 v28, v28
	v_exp_f32_e32 v29, v29
	v_pk_mul_f32 v[32:33], v[32:33], v[34:35] op_sel_hi:[1,0]
	v_min_f32_e32 v26, v26, v246
	v_add_f32_e32 v28, 1.0, v28
	v_add_f32_e32 v29, 1.0, v29
	v_rcp_f32_e32 v28, v28
	v_rcp_f32_e32 v29, v29
	v_min_f32_e32 v30, v33, v246
	v_min_f32_e32 v27, v27, v246
	v_exp_f32_e32 v26, v26
	v_cvt_pk_bf16_f32 v28, v28, v29
	v_min_f32_e32 v29, v32, v246
	v_exp_f32_e32 v30, v30
	v_exp_f32_e32 v29, v29
	v_exp_f32_e32 v27, v27
	v_add_f32_e32 v26, 1.0, v26
	v_add_f32_e32 v30, 1.0, v30
	v_add_f32_e32 v29, 1.0, v29
	v_add_f32_e32 v27, 1.0, v27
	v_rcp_f32_e32 v29, v29
	v_rcp_f32_e32 v30, v30
	v_rcp_f32_e32 v26, v26
	v_rcp_f32_e32 v27, v27
	v_pk_mul_f32 v[22:23], v[22:23], v[34:35] op_sel_hi:[1,0]
	v_cvt_pk_bf16_f32 v29, v29, v30
	v_pk_mul_f32 v[24:25], v[24:25], v[34:35] op_sel_hi:[1,0]
	v_cvt_pk_bf16_f32 v30, v26, v27
	v_min_f32_e32 v26, v36, v246
	v_min_f32_e32 v27, v37, v246
	s_nop 0
	v_exp_f32_e32 v26, v26
	v_exp_f32_e32 v27, v27
	v_add_f32_e32 v26, 1.0, v26
	v_add_f32_e32 v27, 1.0, v27
	v_rcp_f32_e32 v26, v26
	v_rcp_f32_e32 v27, v27
	s_nop 0
	v_cvt_pk_bf16_f32 v31, v26, v27
	v_add_co_u32_e32 v26, vcc, s0, v122
	s_mov_b64 s[0:1], -1
	s_nop 0
	v_addc_co_u32_e32 v27, vcc, 0, v123, vcc
	global_store_dwordx4 v[26:27], v[28:31], off
	s_andn2_b64 vcc, exec, s[38:39]
	s_nop 0
	v_pk_mul_f32 v[28:29], v[20:21], v[34:35] op_sel_hi:[1,0]
	v_pk_mul_f32 v[20:21], v[18:19], v[34:35] op_sel_hi:[1,0]
	v_min_f32_e32 v18, v22, v246
	v_min_f32_e32 v19, v23, v246
	v_min_f32_e32 v22, v25, v246
	s_nop 0
	v_exp_f32_e32 v18, v18
	v_exp_f32_e32 v19, v19
	v_min_f32_e32 v20, v20, v246
	v_min_f32_e32 v21, v21, v246
	v_add_f32_e32 v18, 1.0, v18
	v_add_f32_e32 v19, 1.0, v19
	v_rcp_f32_e32 v18, v18
	v_rcp_f32_e32 v19, v19
	v_exp_f32_e32 v22, v22
	v_exp_f32_e32 v20, v20
	v_exp_f32_e32 v21, v21
	v_cvt_pk_bf16_f32 v18, v18, v19
	v_min_f32_e32 v19, v24, v246
	v_add_f32_e32 v22, 1.0, v22
	v_exp_f32_e32 v19, v19
	v_add_f32_e32 v20, 1.0, v20
	v_add_f32_e32 v21, 1.0, v21
	v_rcp_f32_e32 v22, v22
	v_add_f32_e32 v19, 1.0, v19
	v_rcp_f32_e32 v19, v19
	v_rcp_f32_e32 v20, v20
	v_rcp_f32_e32 v21, v21
	v_cvt_pk_bf16_f32 v19, v19, v22
	v_min_f32_e32 v22, v29, v246
	v_cvt_pk_bf16_f32 v20, v20, v21
	v_min_f32_e32 v21, v28, v246
	v_exp_f32_e32 v22, v22
	v_exp_f32_e32 v21, v21
	v_add_f32_e32 v22, 1.0, v22
	v_add_f32_e32 v21, 1.0, v21
	v_rcp_f32_e32 v21, v21
	v_rcp_f32_e32 v22, v22
	s_nop 0
	v_cvt_pk_bf16_f32 v21, v21, v22
	global_store_dwordx4 v[26:27], v[18:21], off offset:1024
	s_nop 1
	v_mul_f32_e32 v18, 0xbfb8aa3b, v140
	v_pk_mul_f32 v[14:15], v[14:15], v[18:19] op_sel_hi:[1,0]
	v_pk_mul_f32 v[20:21], v[12:13], v[18:19] op_sel_hi:[1,0]
	v_pk_mul_f32 v[12:13], v[10:11], v[18:19] op_sel_hi:[1,0]
	v_min_f32_e32 v10, v14, v246
	v_min_f32_e32 v11, v15, v246
	v_pk_mul_f32 v[16:17], v[16:17], v[18:19] op_sel_hi:[1,0]
	v_exp_f32_e32 v10, v10
	v_exp_f32_e32 v11, v11
	v_min_f32_e32 v14, v17, v246
	v_min_f32_e32 v12, v12, v246
	v_add_f32_e32 v10, 1.0, v10
	v_add_f32_e32 v11, 1.0, v11
	v_rcp_f32_e32 v10, v10
	v_rcp_f32_e32 v11, v11
	v_min_f32_e32 v13, v13, v246
	v_exp_f32_e32 v14, v14
	v_exp_f32_e32 v12, v12
	v_cvt_pk_bf16_f32 v10, v10, v11
	v_min_f32_e32 v11, v16, v246
	v_exp_f32_e32 v13, v13
	v_exp_f32_e32 v11, v11
	v_add_f32_e32 v14, 1.0, v14
	v_add_f32_e32 v12, 1.0, v12
	v_add_f32_e32 v13, 1.0, v13
	v_add_f32_e32 v11, 1.0, v11
	v_rcp_f32_e32 v11, v11
	v_rcp_f32_e32 v14, v14
	v_rcp_f32_e32 v12, v12
	v_rcp_f32_e32 v13, v13
	v_pk_mul_f32 v[6:7], v[6:7], v[18:19] op_sel_hi:[1,0]
	v_cvt_pk_bf16_f32 v11, v11, v14
	v_min_f32_e32 v14, v21, v246
	v_cvt_pk_bf16_f32 v12, v12, v13
	v_min_f32_e32 v13, v20, v246
	v_exp_f32_e32 v14, v14
	v_exp_f32_e32 v13, v13
	v_pk_mul_f32 v[8:9], v[8:9], v[18:19] op_sel_hi:[1,0]
	v_add_f32_e32 v14, 1.0, v14
	v_add_f32_e32 v13, 1.0, v13
	v_rcp_f32_e32 v13, v13
	v_rcp_f32_e32 v14, v14
	s_nop 0
	v_cvt_pk_bf16_f32 v13, v13, v14
	global_store_dwordx4 v[26:27], v[10:13], off offset:2048
	s_nop 1
	v_pk_mul_f32 v[10:11], v[4:5], v[18:19] op_sel_hi:[1,0]
	v_pk_mul_f32 v[4:5], v[2:3], v[18:19] op_sel_hi:[1,0]
	v_min_f32_e32 v2, v6, v246
	v_min_f32_e32 v3, v7, v246
	v_min_f32_e32 v6, v9, v246
	s_nop 0
	v_exp_f32_e32 v2, v2
	v_exp_f32_e32 v3, v3
	v_min_f32_e32 v4, v4, v246
	v_min_f32_e32 v5, v5, v246
	v_add_f32_e32 v2, 1.0, v2
	v_add_f32_e32 v3, 1.0, v3
	v_rcp_f32_e32 v2, v2
	v_rcp_f32_e32 v3, v3
	v_exp_f32_e32 v6, v6
	v_exp_f32_e32 v4, v4
	v_exp_f32_e32 v5, v5
	v_cvt_pk_bf16_f32 v2, v2, v3
	v_min_f32_e32 v3, v8, v246
	v_add_f32_e32 v6, 1.0, v6
	v_exp_f32_e32 v3, v3
	v_add_f32_e32 v4, 1.0, v4
	v_add_f32_e32 v5, 1.0, v5
	v_rcp_f32_e32 v6, v6
	v_add_f32_e32 v3, 1.0, v3
	v_rcp_f32_e32 v3, v3
	v_rcp_f32_e32 v4, v4
	v_rcp_f32_e32 v5, v5
	v_cvt_pk_bf16_f32 v3, v3, v6
	v_min_f32_e32 v6, v11, v246
	v_cvt_pk_bf16_f32 v4, v4, v5
	v_min_f32_e32 v5, v10, v246
	v_exp_f32_e32 v6, v6
	v_exp_f32_e32 v5, v5
	v_add_f32_e32 v6, 1.0, v6
	v_add_f32_e32 v5, 1.0, v5
	v_rcp_f32_e32 v5, v5
	v_rcp_f32_e32 v6, v6
	s_nop 0
	v_cvt_pk_bf16_f32 v5, v5, v6
	global_store_dwordx4 v[26:27], v[2:5], off offset:3072
	s_cbranch_vccnz .LBB0_328
	s_andn2_b64 vcc, exec, s[6:7]
	s_cbranch_vccnz .LBB0_327
	s_barrier
	s_branch .LBB0_327

; #define LAS __attribute__((address_space(3)))
; template <int NP> __device__ __forceinline__ void row_scales(float (&rs)[2][4], const float* base, long row0, int fq, float inv_n) {
;     float t[2][4];
; #pragma unroll
;     for (int ai = 0; ai < 2; ++ai)
; #pragma unroll
;         for (int m = 0; m < 4; ++m) { const long row = row0 + ai * 128 + m * 16;
;             if (NP == 16) { const f32x4 v = *(const f32x4*)(base + row * 16 + 4 * fq); t[ai][m] = (v.x + v.y) + (v.z + v.w); }
;             else if (NP == 8) { const f32x2 v = *(const f32x2*)(base + row * 8 + 2 * fq); t[ai][m] = v.x + v.y; }
;             else t[ai][m] = base[row * 4 + fq]; }
; #pragma unroll
;     for (int ai = 0; ai < 2; ++ai)
; #pragma unroll
;         for (int m = 0; m < 4; ++m) rs[ai][m] = rsqrtf(red_fq(t[ai][m]) * inv_n + EPS);
;     __device__ __forceinline__ void operator()(AccT& acc, const Unit& u, int wr, int wc, int fr, int fq, LAS unsigned char*) const {
;         const long row0 = (long)u.pm * 256 + wr * 64 + fr;
;         float rsa[2][4]; row_scales<16>(rsa, ssqx, row0, fq, 1.f / 1024.f);
; #pragma unroll
;         for (int ai = 0; ai < 2; ++ai)
; #pragma unroll
;             for (int m = 0; m < 4; ++m) {
;                 const long row = row0 + ai * 128 + m * 16;
;                 const float rs = rsa[ai][m];
;                 f32x4 v[2][2];
; #pragma unroll
;                 for (int bj = 0; bj < 2; ++bj)
; #pragma unroll
;                     for (int n = 0; n < 2; ++n) v[bj][n] = acc[ai][bj][m][n] * rs;
;                 const int cl = wc * 32 + 8 * fq;
;                 if (u.pn == 0 || u.pn == 2 || u.pn == 5 || u.pn == 6) {
.LBB0_640:
	s_ashr_i32 s1, s0, 31
	s_lshl_b64 s[0:1], s[0:1], 8
	v_lshl_add_u64 v[156:157], s[0:1], 0, v[136:137]
	v_lshlrev_b64 v[176:177], 6, v[156:157]
	v_lshl_add_u64 v[170:171], v[144:145], 0, v[176:177]
	global_load_dwordx4 v[158:161], v[170:171], off
	s_movk_i32 s0, 0x2000
	v_add_co_u32_e32 v178, vcc, s0, v170
	s_mov_b32 s0, 0x3a800000
	s_nop 0
	v_addc_co_u32_e32 v179, vcc, 0, v171, vcc
	global_load_dwordx4 v[208:211], v[170:171], off offset:1024
	global_load_dwordx4 v[212:215], v[170:171], off offset:2048
	global_load_dwordx4 v[216:219], v[170:171], off offset:3072
	global_load_dwordx4 v[220:223], v[178:179], off
	global_load_dwordx4 v[224:227], v[178:179], off offset:1024
	global_load_dwordx4 v[228:231], v[178:179], off offset:2048
	global_load_dwordx4 v[232:235], v[178:179], off offset:3072
	global_load_dwordx4 v[200:203], v1, s[90:91]
	s_cmp_lg_u32 s18, 0
	s_cselect_b64 s[16:17], -1, 0
	s_cmp_eq_u32 s18, 3
	s_cselect_b64 s[42:43], -1, 0
	s_mov_b64 s[8:9], -1
	s_mov_b64 s[22:23], 0
	s_cmp_lt_i32 s18, 2
	s_mov_b64 s[12:13], 0
	s_mov_b64 s[78:79], 0
	s_waitcnt vmcnt(8)
	v_mov_b32_e32 v162, v159
	v_mov_b32_e32 v163, v160
	v_mov_b32_e32 v159, v161
	v_pk_add_f32 v[158:159], v[162:163], v[158:159]
	s_nop 0
	v_pk_add_f32 v[162:163], v[158:159], v[158:159] op_sel:[0,1] op_sel_hi:[1,0]
	s_waitcnt vmcnt(7)
	v_mov_b64_e32 v[158:159], v[208:209]
	v_mov_b64_e32 v[160:161], v[210:211]
	v_mov_b32_e32 v0, v162
	s_nop 1
	v_permlane16_swap_b32_e32 v162, v0
	v_mov_b32_e32 v164, v159
	v_mov_b32_e32 v165, v160
	v_mov_b32_e32 v159, v161
	v_pk_add_f32 v[158:159], v[164:165], v[158:159]
	s_nop 0
	v_pk_add_f32 v[166:167], v[158:159], v[158:159] op_sel:[0,1] op_sel_hi:[1,0]
	s_waitcnt vmcnt(6)
	v_mov_b64_e32 v[158:159], v[212:213]
	v_mov_b64_e32 v[160:161], v[214:215]
	v_mov_b32_e32 v164, v159
	v_mov_b32_e32 v165, v160
	v_mov_b32_e32 v159, v161
	v_pk_add_f32 v[158:159], v[164:165], v[158:159]
	s_nop 0
	v_pk_add_f32 v[168:169], v[158:159], v[158:159] op_sel:[0,1] op_sel_hi:[1,0]
	s_waitcnt vmcnt(5)
	v_mov_b64_e32 v[158:159], v[216:217]
	v_mov_b64_e32 v[160:161], v[218:219]
	v_mov_b32_e32 v164, v159
	v_mov_b32_e32 v165, v160
	v_mov_b32_e32 v159, v161
	v_pk_add_f32 v[158:159], v[164:165], v[158:159]
	s_nop 0
	v_pk_add_f32 v[164:165], v[158:159], v[158:159] op_sel:[0,1] op_sel_hi:[1,0]
	s_waitcnt vmcnt(4)
	v_mov_b64_e32 v[158:159], v[220:221]
	v_mov_b64_e32 v[160:161], v[222:223]
	v_mov_b32_e32 v170, v159
	v_mov_b32_e32 v171, v160
	v_mov_b32_e32 v159, v161
	v_pk_add_f32 v[158:159], v[170:171], v[158:159]
	s_nop 0
	v_pk_add_f32 v[170:171], v[158:159], v[158:159] op_sel:[0,1] op_sel_hi:[1,0]
	s_waitcnt vmcnt(3)
	v_mov_b64_e32 v[158:159], v[224:225]
	v_mov_b64_e32 v[160:161], v[226:227]
	v_mov_b32_e32 v172, v159
	v_mov_b32_e32 v173, v160
	v_mov_b32_e32 v159, v161
	v_pk_add_f32 v[158:159], v[172:173], v[158:159]
	s_waitcnt vmcnt(2)
	v_mov_b64_e32 v[172:173], v[228:229]
	v_mov_b64_e32 v[174:175], v[230:231]
	v_pk_add_f32 v[158:159], v[158:159], v[158:159] op_sel:[0,1] op_sel_hi:[1,0]
	v_mov_b32_e32 v160, v173
	v_mov_b32_e32 v161, v174
	v_mov_b32_e32 v173, v175
	v_pk_add_f32 v[160:161], v[160:161], v[172:173]
	s_waitcnt vmcnt(0)
	v_mov_b64_e32 v[172:173], v[232:233]
	v_mov_b64_e32 v[174:175], v[234:235]
	v_pk_add_f32 v[160:161], v[160:161], v[160:161] op_sel:[0,1] op_sel_hi:[1,0]
	v_mov_b32_e32 v178, v173
	v_mov_b32_e32 v179, v174
	v_mov_b32_e32 v173, v175
	v_pk_add_f32 v[172:173], v[178:179], v[172:173]
	s_nop 0
	v_pk_add_f32 v[178:179], v[172:173], v[172:173] op_sel:[0,1] op_sel_hi:[1,0]
	v_add_f32_e32 v173, v162, v0
	v_mov_b32_e32 v0, v166
	s_nop 1
	v_permlane16_swap_b32_e32 v166, v0
	v_add_f32_e32 v172, v166, v0
	v_mov_b32_e32 v0, v168
	s_nop 1
	v_permlane16_swap_b32_e32 v168, v0
	v_add_f32_e32 v167, v168, v0
	v_mov_b32_e32 v0, v164
	s_nop 1
	v_permlane16_swap_b32_e32 v164, v0
	v_add_f32_e32 v166, v164, v0
	v_mov_b32_e32 v0, v170
	s_nop 1
	v_permlane16_swap_b32_e32 v170, v0
	v_add_f32_e32 v163, v170, v0
	v_mov_b32_e32 v0, v158
	s_nop 1
	v_permlane16_swap_b32_e32 v158, v0
	v_add_f32_e32 v162, v158, v0
	v_mov_b32_e32 v0, v160
	s_nop 1
	v_permlane16_swap_b32_e32 v160, v0
	v_mov_b32_e32 v175, v173
	v_mov_b32_e32 v174, v172
	v_add_f32_e32 v159, v160, v0
	v_mov_b32_e32 v0, v178
	v_permlane32_swap_b32_e32 v173, v175
	v_permlane32_swap_b32_e32 v172, v174
	v_permlane16_swap_b32_e32 v178, v0
	v_add_f32_e32 v158, v178, v0
	v_pk_add_f32 v[170:171], v[172:173], v[174:175]
	v_mov_b32_e32 v169, v167
	v_mov_b32_e32 v168, v166
	v_mov_b32_e32 v165, v163
	v_mov_b32_e32 v164, v162
	v_mov_b32_e32 v161, v159
	v_mov_b32_e32 v160, v158
	v_pk_fma_f32 v[170:171], v[170:171], s[0:1], v[194:195] op_sel_hi:[1,0,0]
	v_permlane32_swap_b32_e32 v167, v169
	v_permlane32_swap_b32_e32 v166, v168
	v_permlane32_swap_b32_e32 v163, v165
	v_permlane32_swap_b32_e32 v162, v164
	v_permlane32_swap_b32_e32 v159, v161
	v_permlane32_swap_b32_e32 v158, v160
	v_cmp_gt_f32_e64 s[44:45], s33, v170
	v_cmp_gt_f32_e64 s[0:1], s33, v171
	s_cbranch_scc1 .LBB0_653
	s_cmp_gt_i32 s18, 4
	s_cbranch_scc0 .LBB0_647
	s_cmp_gt_i32 s18, 5
	s_cbranch_scc0 .LBB0_648
	s_mov_b64 s[78:79], -1
	s_mov_b64 s[8:9], 0
	s_cmp_eq_u32 s18, 6
	s_cbranch_scc0 .LBB0_645
	v_readlane_b32 s12, v255, 48
	v_lshlrev_b64 v[172:173], 9, v[156:157]
	v_readlane_b32 s13, v255, 49
	s_mov_b64 s[78:79], 0
	s_nop 0
	v_lshl_add_u64 v[172:173], s[12:13], 0, v[172:173]
	s_mov_b64 s[12:13], -1
